# attention tile loop edge: next K/V tile loads, the skip test and the K read address are issued in front of the tile barrier instead of after it (loop-edge rotation)
# baseline (speedup 1.0000x reference)
; __device__ __forceinline__ int mk_tid() { int t = threadIdx.x; asm volatile("" : "+v"(t)); return t; }
; #define LAS __attribute__((address_space(3)))
; __device__ __forceinline__ void dattn_unit(LAS unsigned char* lds, int b, int h, int qb, const bf16* Q, const bf16* K, const bf16* V, bf16* YB, float lam, const float* subg, float oml, int tid) {
;     tid = mk_tid();
;     const int lane = tid & 63, w = __builtin_amdgcn_readfirstlane(tid >> 6), ql = lane & 31, hi = lane >> 5;
;     const LAS float* tab = (const LAS float*)(lds + AT_TAB);
;     const size_t rowb = (size_t)b * SEQ;
;     const int qmin = qb * 256 + w * 32, q = qmin + ql, qmax = qmin + 31;
;     LAS bf16x8* qs = (LAS bf16x8*)(lds + AT_QS) + w * 512 + lane;
; #pragma unroll
;     for (int mp = 0; mp < 2; ++mp)
; #pragma unroll
;         for (int ks = 0; ks < 4; ++ks) qs[(mp * 4 + ks) * 64] = *(const bf16x8*)(Q + (rowb + q) * 1024 + h * 128 + mp * 64 + ks * 16 + hi * 8);
;     f32x16 o[2][4];
; #pragma unroll
;     for (int mp = 0; mp < 2; ++mp)
; #pragma unroll
;         for (int cb = 0; cb < 4; ++cb) o[mp][cb] = f32x16{};
;     float mref[2] = {0.f, 0.f}, lsum[2] = {0.f, 0.f};
;     const int NT = 4 * qb + 4;
;     const bf16* kg = K + (rowb + (tid >> 3)) * 1024 + h * 128 + (tid & 7) * 8;
;     const bf16* vg = V + (rowb + (tid & 63)) * 1024 + h * 128 + (tid >> 6) * 16;
;     v4u kr0 = *(const v4u*)(kg), kr1 = *(const v4u*)(kg + 64), vr0 = *(const v4u*)(vg), vr1 = *(const v4u*)(vg + 8);
;     ...
;     AT_STAGE(0);
;     __syncthreads();
.LBB0_225:
	v_mov_b32_e32 v54, v211
	s_lshl_b32 s19, s35, 8
	v_ashrrev_i32_e32 v52, 6, v54
	v_ashrrev_i32_e32 v48, 3, v54
	v_readfirstlane_b32 s18, v52
	s_lshl_b32 s31, s18, 5
	v_ashrrev_i32_e32 v49, 31, v48
	v_and_b32_e32 v55, 31, v54
	s_add_i32 s31, s31, s19
	v_lshl_add_u64 v[32:33], s[6:7], 0, v[48:49]
	v_lshlrev_b32_e32 v34, 3, v54
	v_or_b32_e32 v178, s31, v55
	v_lshlrev_b64 v[32:33], 11, v[32:33]
	v_and_b32_e32 v34, 56, v34
	v_and_b32_e32 v53, 63, v54
	v_ashrrev_i32_e32 v179, 31, v178
	v_lshl_add_u64 v[32:33], s[10:11], 0, v[32:33]
	v_lshlrev_b32_e32 v180, 1, v34
	v_mov_b32_e32 v181, v209
	v_lshl_add_u64 v[0:1], s[6:7], 0, v[178:179]
	v_lshl_add_u64 v[36:37], v[32:33], 0, v[180:181]
	v_or_b32_e32 v32, s6, v53
	v_mov_b32_e32 v33, s7
	v_lshlrev_b32_e32 v34, 4, v52
	v_bfe_u32 v194, v54, 5, 1
	v_lshlrev_b64 v[0:1], 11, v[0:1]
	v_lshlrev_b64 v[32:33], 11, v[32:33]
	v_ashrrev_i32_e32 v35, 31, v34
	v_lshl_add_u64 v[176:177], s[8:9], 0, v[0:1]
	v_lshlrev_b32_e32 v208, 4, v194
	v_lshl_add_u64 v[32:33], s[20:21], 0, v[32:33]
	v_lshlrev_b64 v[50:51], 1, v[34:35]
	v_lshl_add_u64 v[28:29], v[176:177], 0, v[208:209]
	v_lshl_add_u64 v[44:45], v[32:33], 0, v[50:51]
	global_load_dwordx4 v[0:3], v[28:29], off
	global_load_dwordx4 v[4:7], v[28:29], off offset:32
	global_load_dwordx4 v[8:11], v[28:29], off offset:64
	global_load_dwordx4 v[12:15], v[28:29], off offset:96
	global_load_dwordx4 v[16:19], v[28:29], off offset:128
	global_load_dwordx4 v[20:23], v[28:29], off offset:160
	global_load_dwordx4 v[24:27], v[28:29], off offset:192
	s_nop 0
	global_load_dwordx4 v[28:31], v[28:29], off offset:224
	s_nop 0
	global_load_dwordx4 v[32:35], v[36:37], off
	s_nop 0
	global_load_dwordx4 v[36:39], v[36:37], off offset:128
	s_nop 0
	global_load_dwordx4 v[40:43], v[44:45], off
	s_nop 0
	global_load_dwordx4 v[44:47], v[44:45], off offset:16
	s_lshl_b32 s19, s35, 10
	s_or_b32 s56, s19, 0x300
	s_movk_i32 s19, 0x48
	s_lshl_b32 s18, s18, 13
	v_mul_lo_u32 v56, v48, s19
	s_movk_i32 s19, 0x480
	s_add_i32 s18, s18, 0
	v_mul_lo_u32 v57, v52, s19
	v_lshlrev_b32_e32 v195, 1, v53
	v_lshrrev_b32_e32 v58, 2, v53
	v_lshrrev_b32_e32 v59, 3, v53
	v_xor_b32_e32 v58, v58, v59
	v_and_b32_e32 v58, 1, v58
	v_mul_u32_u24_e32 v58, 24, v58
	v_xor_b32_e32 v195, v195, v58
	v_lshlrev_b32_e32 v52, 11, v53
	v_lshl_add_u32 v53, v53, 4, s18
	v_lshlrev_b32_e32 v196, 1, v56
	v_lshlrev_b32_e32 v197, 1, v57
	v_add_u32_e32 v189, 0x12400, v53
	v_mov_b32_e32 v53, v209
	v_mul_u32_u24_e32 v192, 0x90, v55
	v_add3_u32 v55, 0, v196, v180
	v_add3_u32 v56, 0, v197, v195
	v_lshlrev_b32_e32 v193, 4, v194
	s_or_b32 s35, s31, 31
	s_mov_b32 s57, 0
	v_mov_b32_e32 v179, 0
	s_movk_i32 s58, 0xb0
	v_mov_b32_e32 v181, 0
	v_mov_b32_e32 v190, 0
	v_mov_b32_e32 v191, 0
	s_mov_b32 s59, 0
	s_waitcnt vmcnt(11)
	ds_write_b128 v189, v[0:3]
	s_waitcnt vmcnt(10)
	ds_write_b128 v189, v[4:7] offset:1024
	s_waitcnt vmcnt(9)
	ds_write_b128 v189, v[8:11] offset:2048
	s_waitcnt vmcnt(8)
	ds_write_b128 v189, v[12:15] offset:3072
	s_waitcnt vmcnt(7)
	ds_write_b128 v189, v[16:19] offset:4096
	s_waitcnt vmcnt(6)
	ds_write_b128 v189, v[20:23] offset:5120
	s_waitcnt vmcnt(5)
	ds_write_b128 v189, v[24:27] offset:6144
	s_waitcnt vmcnt(4)
	ds_write_b128 v189, v[28:31] offset:7168
	s_waitcnt vmcnt(3)
	ds_write_b128 v55, v[32:35]
	s_waitcnt vmcnt(2)
	ds_write_b128 v55, v[36:39] offset:9216
	s_waitcnt vmcnt(1)
	ds_write_b16 v56, v40 offset:18432
	ds_write_b16_d16_hi v56, v40 offset:18576
	ds_write_b16 v56, v41 offset:18720
	ds_write_b16_d16_hi v56, v41 offset:18864
	ds_write_b16 v56, v42 offset:19008
	ds_write_b16_d16_hi v56, v42 offset:19152
	ds_write_b16 v56, v43 offset:19296
	ds_write_b16_d16_hi v56, v43 offset:19440
	s_waitcnt vmcnt(0)
	ds_write_b16 v56, v44 offset:19584
	ds_write_b16_d16_hi v56, v44 offset:19728
	ds_write_b16 v56, v45 offset:19872
	ds_write_b16_d16_hi v56, v45 offset:20016
	ds_write_b16 v56, v46 offset:20160
	ds_write_b16_d16_hi v56, v46 offset:20304
	ds_write_b16 v56, v47 offset:20448
	ds_write_b16_d16_hi v56, v47 offset:20592
	v_lshl_add_u64 v[0:1], v[52:53], 0, v[50:51]
	v_lshl_add_u64 v[182:183], s[44:45], 0, v[0:1]
	v_lshlrev_b64 v[0:1], 11, v[48:49]
	v_and_b32_e32 v2, 7, v54
	v_lshl_or_b32 v0, v2, 4, v0
	v_lshl_add_u64 v[184:185], s[44:45], 0, v[0:1]
	v_lshlrev_b32_e32 v0, 2, v178
	v_sub_u32_e32 v0, v208, v0
	v_mov_b32_e32 v14, v209
	v_mov_b32_e32 v15, v209
	v_add_u32_e32 v198, 0, v0
	v_mov_b32_e32 v0, v209
	v_mov_b32_e32 v1, v209
	v_mov_b32_e32 v2, v209
	v_mov_b32_e32 v3, v209
	v_mov_b32_e32 v4, v209
	v_mov_b32_e32 v5, v209
	v_mov_b32_e32 v6, v209
	v_mov_b32_e32 v7, v209
	v_mov_b32_e32 v8, v209
	v_mov_b32_e32 v9, v209
	v_mov_b32_e32 v10, v209
	v_mov_b32_e32 v11, v209
	v_mov_b32_e32 v12, v209
	v_mov_b32_e32 v13, v209
	v_mov_b64_e32 v[46:47], v[14:15]
	v_mov_b64_e32 v[78:79], v[14:15]
	v_mov_b64_e32 v[110:111], v[14:15]
	v_mov_b64_e32 v[30:31], v[14:15]
	v_mov_b64_e32 v[62:63], v[14:15]
	v_mov_b64_e32 v[94:95], v[14:15]
	v_mov_b64_e32 v[126:127], v[14:15]
	v_mov_b64_e32 v[44:45], v[12:13]
	v_mov_b64_e32 v[42:43], v[10:11]
	v_mov_b64_e32 v[40:41], v[8:9]
	v_mov_b64_e32 v[38:39], v[6:7]
	v_mov_b64_e32 v[36:37], v[4:5]
	v_mov_b64_e32 v[34:35], v[2:3]
	v_mov_b64_e32 v[32:33], v[0:1]
	v_mov_b64_e32 v[76:77], v[12:13]
	v_mov_b64_e32 v[74:75], v[10:11]
	v_mov_b64_e32 v[72:73], v[8:9]
	v_mov_b64_e32 v[70:71], v[6:7]
	v_mov_b64_e32 v[68:69], v[4:5]
	v_mov_b64_e32 v[66:67], v[2:3]
	v_mov_b64_e32 v[64:65], v[0:1]
	v_mov_b64_e32 v[108:109], v[12:13]
	v_mov_b64_e32 v[106:107], v[10:11]
	v_mov_b64_e32 v[104:105], v[8:9]
	v_mov_b64_e32 v[102:103], v[6:7]
	v_mov_b64_e32 v[100:101], v[4:5]
	v_mov_b64_e32 v[98:99], v[2:3]
; #define LAS __attribute__((address_space(3)))
; __device__ __forceinline__ void dattn_unit(LAS unsigned char* lds, int b, int h, int qb, const bf16* Q, const bf16* K, const bf16* V, bf16* YB, float lam, const float* subg, float oml, int tid) {
;     ...
;     __syncthreads();
;     for (int t = 0; t < NT; ++t) {
;         if (t + 1 < NT) { const size_t adv = (size_t)(t + 1) * 64 * 1024; kr0 = *(const v4u*)(kg + adv); kr1 = *(const v4u*)(kg + adv + 64); vr0 = *(const v4u*)(vg + adv); vr1 = *(const v4u*)(vg + adv + 8); }
;         const LAS bf16* Ks = (const LAS bf16*)(lds + (t & 1) * AT_BUF + AT_KS); const LAS bf16* Vt = (const LAS bf16*)(lds + (t & 1) * AT_BUF + AT_VT);
;         const int kvbase = t * 64;
;         if (kvbase <= qmax) {
;     ...
;             if (need_bm) { const LAS float* gb = tab + (159 - (q - (kvbase + 32 * sub + 4 * hi)));
; #pragma unroll
;                 for (int r = 0; r < 16; ++r) { const float bv = gb[(r & 3) + 8 * (r >> 2)]; s0[r] += bv; s1[r] += bv; } }
	v_mov_b64_e32 v[96:97], v[0:1]
	v_mov_b64_e32 v[28:29], v[12:13]
	v_mov_b64_e32 v[26:27], v[10:11]
	v_mov_b64_e32 v[24:25], v[8:9]
	v_mov_b64_e32 v[22:23], v[6:7]
	v_mov_b64_e32 v[20:21], v[4:5]
	v_mov_b64_e32 v[18:19], v[2:3]
	v_mov_b64_e32 v[16:17], v[0:1]
	v_mov_b64_e32 v[60:61], v[12:13]
	v_mov_b64_e32 v[58:59], v[10:11]
	v_mov_b64_e32 v[56:57], v[8:9]
	v_mov_b64_e32 v[54:55], v[6:7]
	v_mov_b64_e32 v[52:53], v[4:5]
	v_mov_b64_e32 v[50:51], v[2:3]
	v_mov_b64_e32 v[48:49], v[0:1]
	v_mov_b64_e32 v[92:93], v[12:13]
	v_mov_b64_e32 v[90:91], v[10:11]
	v_mov_b64_e32 v[88:89], v[8:9]
	v_mov_b64_e32 v[86:87], v[6:7]
	v_mov_b64_e32 v[84:85], v[4:5]
	v_mov_b64_e32 v[82:83], v[2:3]
	v_mov_b64_e32 v[80:81], v[0:1]
	v_mov_b64_e32 v[124:125], v[12:13]
	v_mov_b64_e32 v[122:123], v[10:11]
	v_mov_b64_e32 v[120:121], v[8:9]
	v_mov_b64_e32 v[118:119], v[6:7]
	v_mov_b64_e32 v[116:117], v[4:5]
	v_mov_b64_e32 v[114:115], v[2:3]
	v_mov_b64_e32 v[112:113], v[0:1]
	s_add_u32 s98, s16, 0x1b020000
	s_addc_u32 s99, s17, 0
	s_add_u32 s100, s16, 0xb020000
	s_addc_u32 s101, s17, 0
	s_mov_b32 s60, 0
	v_add3_u32 v199, s60, v208, v192
	v_lshl_add_u64 v[128:129], v[184:185], 0, s[98:99]
	v_lshl_add_u64 v[130:131], v[182:183], 0, s[100:101]
	global_load_dwordx4 v[168:171], v[128:129], off
	global_load_dwordx4 v[172:175], v[128:129], off offset:128
	global_load_dwordx4 v[164:167], v[130:131], off
	global_load_dwordx4 v[160:163], v[130:131], off offset:16
	s_add_i32 s18, s58, 0xffffff50
	s_waitcnt lgkmcnt(0)
	s_cmp_gt_i32 s18, s35
	s_barrier
	s_branch .LBB0_227
.Lattn_exit:
	s_barrier
	s_branch .LBB0_249
.Lqk_diag0:
	s_waitcnt lgkmcnt(4)
	v_mfma_f32_32x32x16_bf16 v[128:143], v[204:207], v[238:241], v[128:143]
	s_waitcnt lgkmcnt(1)
	v_mfma_f32_32x32x16_bf16 v[144:159], v[222:225], v[230:233], v[144:159]
	s_waitcnt lgkmcnt(0)
	v_mfma_f32_32x32x16_bf16 v[128:143], v[226:229], v[234:237], v[128:143]
	v_add_u32_e32 v200, s57, v198
	v_add_u32_e32 v212, 0x1227c, v200
	v_add_u32_e32 v214, 0x12284, v200
	v_add_u32_e32 v218, 0x1229c, v200
	v_add_u32_e32 v220, 0x122a4, v200
	v_add_u32_e32 v201, 0x122bc, v200
	v_add_u32_e32 v202, 0x122c4, v200
	v_add_u32_e32 v204, 0x122dc, v200
	v_add_u32_e32 v206, 0x122e4, v200
	ds_read2_b32 v[200:201], v201 offset1:1
	ds_read2_b32 v[202:203], v202 offset1:1
	ds_read2_b32 v[204:205], v204 offset1:1
	ds_read2_b32 v[206:207], v206 offset1:1
	ds_read2_b32 v[212:213], v212 offset1:1
	ds_read2_b32 v[214:215], v214 offset1:1
	ds_read2_b32 v[218:219], v218 offset1:1
	ds_read2_b32 v[220:221], v220 offset1:1
	s_waitcnt lgkmcnt(4)
	v_pk_add_f32 v[158:159], v[158:159], v[206:207]
	v_pk_add_f32 v[156:157], v[156:157], v[204:205]
	v_pk_add_f32 v[154:155], v[154:155], v[202:203]
	v_pk_add_f32 v[152:153], v[152:153], v[200:201]
	s_waitcnt lgkmcnt(0)
	v_pk_add_f32 v[150:151], v[150:151], v[220:221]
	v_pk_add_f32 v[148:149], v[148:149], v[218:219]
	v_pk_add_f32 v[146:147], v[146:147], v[214:215]
	v_pk_add_f32 v[144:145], v[144:145], v[212:213]
	v_pk_add_f32 v[142:143], v[142:143], v[206:207]
	v_pk_add_f32 v[140:141], v[140:141], v[204:205]
	v_pk_add_f32 v[138:139], v[138:139], v[202:203]
	v_pk_add_f32 v[136:137], v[136:137], v[200:201]
	v_pk_add_f32 v[134:135], v[134:135], v[220:221]
	v_pk_add_f32 v[132:133], v[132:133], v[218:219]
	v_pk_add_f32 v[130:131], v[130:131], v[214:215]
	v_pk_add_f32 v[128:129], v[128:129], v[212:213]
	v_add3_u32 v219, s60, v193, v192
	ds_read_b128 v[228:231], v219 offset:23040
	ds_read_b128 v[232:235], v219 offset:23072
	ds_read_b128 v[236:239], v219 offset:27648
	ds_read_b128 v[240:243], v219 offset:27680
	ds_read_b128 v[212:215], v219 offset:32256
	ds_read_b128 v[220:223], v219 offset:18432
	s_branch .Lsm0_0
.Lqk_diag1:
	s_waitcnt lgkmcnt(4)
	v_mfma_f32_32x32x16_bf16 v[128:143], v[218:221], v[212:215], v[128:143]
	s_waitcnt lgkmcnt(1)
	v_mfma_f32_32x32x16_bf16 v[144:159], v[226:229], v[234:237], v[144:159]
	s_waitcnt lgkmcnt(0)
	v_mfma_f32_32x32x16_bf16 v[128:143], v[230:233], v[238:241], v[128:143]
	v_add_u32_e32 v199, s57, v198
	v_add_u32_e32 v218, 0x122fc, v199
	v_add_u32_e32 v220, 0x12304, v199
	v_add_u32_e32 v222, 0x1231c, v199
	v_add_u32_e32 v224, 0x12324, v199
	v_add_u32_e32 v204, 0x1233c, v199
	v_add_u32_e32 v206, 0x12344, v199
	v_add_u32_e32 v212, 0x1235c, v199
	v_add_u32_e32 v199, 0x12364, v199
	ds_read2_b32 v[204:205], v204 offset1:1
	ds_read2_b32 v[206:207], v206 offset1:1
	ds_read2_b32 v[212:213], v212 offset1:1
	ds_read2_b32 v[214:215], v199 offset1:1
	ds_read2_b32 v[218:219], v218 offset1:1
	ds_read2_b32 v[220:221], v220 offset1:1
	ds_read2_b32 v[222:223], v222 offset1:1
	ds_read2_b32 v[224:225], v224 offset1:1
	s_waitcnt lgkmcnt(4)
	v_pk_add_f32 v[158:159], v[158:159], v[214:215]
	v_pk_add_f32 v[156:157], v[156:157], v[212:213]
	v_pk_add_f32 v[154:155], v[154:155], v[206:207]
	v_pk_add_f32 v[152:153], v[152:153], v[204:205]
	s_waitcnt lgkmcnt(0)
	v_pk_add_f32 v[150:151], v[150:151], v[224:225]
	v_pk_add_f32 v[148:149], v[148:149], v[222:223]
	v_pk_add_f32 v[146:147], v[146:147], v[220:221]
	v_pk_add_f32 v[144:145], v[144:145], v[218:219]
	v_pk_add_f32 v[142:143], v[142:143], v[214:215]
	v_pk_add_f32 v[140:141], v[140:141], v[212:213]
	v_pk_add_f32 v[138:139], v[138:139], v[206:207]
	v_pk_add_f32 v[136:137], v[136:137], v[204:205]
	v_pk_add_f32 v[134:135], v[134:135], v[224:225]
	v_pk_add_f32 v[132:133], v[132:133], v[222:223]
	v_pk_add_f32 v[130:131], v[130:131], v[220:221]
	v_pk_add_f32 v[128:129], v[128:129], v[218:219]
	v_add3_u32 v243, s60, v193, v192
	ds_read_b128 v[222:225], v243 offset:23104
	ds_read_b128 v[226:229], v243 offset:23136
	ds_read_b128 v[230:233], v243 offset:27712
	ds_read_b128 v[234:237], v243 offset:27744
	ds_read_b128 v[238:241], v243 offset:32320
	ds_read_b128 v[212:215], v243 offset:18496
	ds_read_b128 v[200:203], v243 offset:18528
	s_branch .Lsm0_1
; #define LAS __attribute__((address_space(3)))
; __device__ __forceinline__ void dattn_unit(LAS unsigned char* lds, int b, int h, int qb, const bf16* Q, const bf16* K, const bf16* V, bf16* YB, float lam, const float* subg, float oml, int tid) {
;     ...
;         if (t + 1 < NT) { const size_t adv = (size_t)(t + 1) * 64 * 1024; kr0 = *(const v4u*)(kg + adv); kr1 = *(const v4u*)(kg + adv + 64); vr0 = *(const v4u*)(vg + adv); vr1 = *(const v4u*)(vg + adv + 8); }
;         const LAS bf16* Ks = (const LAS bf16*)(lds + (t & 1) * AT_BUF + AT_KS); const LAS bf16* Vt = (const LAS bf16*)(lds + (t & 1) * AT_BUF + AT_VT);
;         const int kvbase = t * 64;
;         if (kvbase <= qmax) {
;     ...
;         if (t + 1 < NT) AT_STAGE((t + 1) & 1);
;         __syncthreads();
.LBB0_226:
	s_add_i32 s59, s59, 1
	s_bitcmp1_b32 s59, 0
	s_cselect_b32 s18, 0x9000, 0
	s_add_i32 s60, s18, 0
	v_add3_u32 v199, s60, v208, v192
	v_add3_u32 v128, s60, v196, v180
	s_addk_i32 s57, 0x100
	s_add_i32 s58, s58, 64
	s_waitcnt vmcnt(3)
	ds_write_b128 v128, v[168:171]
	s_waitcnt vmcnt(2)
	ds_write_b128 v128, v[172:175] offset:9216
	v_add3_u32 v128, s60, v197, v195
	s_add_u32 s98, s98, s14
	s_addc_u32 s99, s99, s15
	s_add_u32 s100, s100, s14
	s_addc_u32 s101, s101, s15
	s_cmp_lg_u32 s56, s57
	s_waitcnt vmcnt(1)
	ds_write_b16 v128, v164 offset:18432
	ds_write_b16_d16_hi v128, v164 offset:18576
	ds_write_b16 v128, v165 offset:18720
	ds_write_b16_d16_hi v128, v165 offset:18864
	ds_write_b16 v128, v166 offset:19008
	ds_write_b16_d16_hi v128, v166 offset:19152
	ds_write_b16 v128, v167 offset:19296
	ds_write_b16_d16_hi v128, v167 offset:19440
	s_waitcnt vmcnt(0)
	ds_write_b16 v128, v160 offset:19584
	ds_write_b16_d16_hi v128, v160 offset:19728
	ds_write_b16 v128, v161 offset:19872
	ds_write_b16_d16_hi v128, v161 offset:20016
	ds_write_b16 v128, v162 offset:20160
	ds_write_b16_d16_hi v128, v162 offset:20304
	ds_write_b16 v128, v163 offset:20448
	ds_write_b16_d16_hi v128, v163 offset:20592
	s_waitcnt lgkmcnt(0)
	s_cbranch_scc0 .Lattn_exit
	v_lshl_add_u64 v[128:129], v[184:185], 0, s[98:99]
	v_lshl_add_u64 v[130:131], v[182:183], 0, s[100:101]
	global_load_dwordx4 v[168:171], v[128:129], off
	global_load_dwordx4 v[172:175], v[128:129], off offset:128
	global_load_dwordx4 v[164:167], v[130:131], off
	global_load_dwordx4 v[160:163], v[130:131], off offset:16
	s_add_i32 s18, s58, 0xffffff50
	s_cmp_gt_i32 s18, s35
	s_barrier
.LBB0_227:
	s_cbranch_scc1 .LBB0_226
	ds_read_b128 v[138:141], v199
	ds_read_b128 v[200:203], v199 offset:9216
	ds_read_b128 v[204:207], v189
	ds_read_b128 v[218:221], v189 offset:4096
	v_xor_b32_e32 v144, 0x80000000, v190
	v_xor_b32_e32 v128, 0x80000000, v191
	v_mov_b32_e32 v145, v144
	v_mov_b64_e32 v[146:147], v[144:145]
	v_mov_b64_e32 v[148:149], v[144:145]
	v_mov_b64_e32 v[150:151], v[144:145]
	v_mov_b64_e32 v[152:153], v[144:145]
	v_mov_b64_e32 v[154:155], v[144:145]
	v_mov_b64_e32 v[156:157], v[144:145]
	v_mov_b64_e32 v[158:159], v[144:145]
	v_mov_b32_e32 v129, v128
	v_mov_b64_e32 v[130:131], v[128:129]
	v_mov_b64_e32 v[132:133], v[128:129]
	v_mov_b64_e32 v[134:135], v[128:129]
	v_mov_b64_e32 v[136:137], v[128:129]
	ds_read_b128 v[222:225], v199 offset:32
	ds_read_b128 v[226:229], v199 offset:9248
	ds_read_b128 v[230:233], v189 offset:1024
	ds_read_b128 v[234:237], v189 offset:5120
	s_waitcnt lgkmcnt(5)
	v_mfma_f32_32x32x16_bf16 v[144:159], v[138:141], v[204:207], v[144:159]
	v_mov_b64_e32 v[142:143], v[128:129]
	v_mov_b64_e32 v[138:139], v[128:129]
	v_mov_b64_e32 v[140:141], v[128:129]
	s_sub_i32 s18, s58, 32
	s_cmp_le_i32 s18, s31
	s_waitcnt lgkmcnt(4)
	v_mfma_f32_32x32x16_bf16 v[128:143], v[200:203], v[218:221], v[128:143]
	ds_read_b128 v[200:203], v199 offset:64
	ds_read_b128 v[204:207], v199 offset:9280
	ds_read_b128 v[218:221], v189 offset:2048
	ds_read_b128 v[238:241], v189 offset:6144
	s_waitcnt lgkmcnt(5)
	v_mfma_f32_32x32x16_bf16 v[144:159], v[222:225], v[230:233], v[144:159]
	s_waitcnt lgkmcnt(4)
	v_mfma_f32_32x32x16_bf16 v[128:143], v[226:229], v[234:237], v[128:143]
	ds_read_b128 v[222:225], v199 offset:96
	ds_read_b128 v[226:229], v199 offset:9312
	ds_read_b128 v[230:233], v189 offset:3072
	ds_read_b128 v[234:237], v189 offset:7168
	s_waitcnt lgkmcnt(5)
	v_mfma_f32_32x32x16_bf16 v[144:159], v[200:203], v[218:221], v[144:159]
	s_cbranch_scc0 .Lqk_diag0
	s_waitcnt lgkmcnt(1)
	v_mfma_f32_32x32x16_bf16 v[144:159], v[222:225], v[230:233], v[144:159]
	v_add3_u32 v219, s60, v193, v192
	ds_read_b128 v[212:215], v219 offset:32256
	ds_read_b128 v[220:223], v219 offset:18432
	v_mfma_f32_32x32x16_bf16 v[128:143], v[204:207], v[238:241], v[128:143]
	s_waitcnt lgkmcnt(2)
	v_mfma_f32_32x32x16_bf16 v[128:143], v[226:229], v[234:237], v[128:143]
	ds_read_b128 v[228:231], v219 offset:23040
	ds_read_b128 v[232:235], v219 offset:23072
	ds_read_b128 v[236:239], v219 offset:27648
	ds_read_b128 v[240:243], v219 offset:27680
	s_nop 1

; #define LAS __attribute__((address_space(3)))
; __device__ __forceinline__ void dattn_unit(LAS unsigned char* lds, int b, int h, int qb, const bf16* Q, const bf16* K, const bf16* V, bf16* YB, float lam, const float* subg, float oml, int tid) {
;     ...
;             if (kvbase + 32 * sub > qmax) continue;
;             const bool need_bm = kvbase + 32 * sub + 31 + 113 > qmin;
;             LAS bf16x8* qsp = qs; asm volatile("" : "+v"(qsp));
;             f32x16 s0, s1;
; #pragma unroll
;             for (int r = 0; r < 16; ++r) { s0[r] = -mref[0]; s1[r] = -mref[1]; }
;             {
;                 const LAS bf16* kp = Ks + (32 * sub + ql) * 72 + hi * 8;
;                 bf16x8 ka = *(const LAS bf16x8*)kp, kb = *(const LAS bf16x8*)(kp + 64 * 72), qa = qsp[0], qb = qsp[4 * 64];
;                 __builtin_amdgcn_sched_group_barrier(0x100, 4, 0);
; #pragma unroll
;                 for (int ks = 0; ks < 4; ++ks) { bf16x8 ka2 = ka, kb2 = kb, qa2 = qa, qb2 = qb;
;                     if (ks < 3) { ka2 = *(const LAS bf16x8*)(kp + (ks + 1) * 16); kb2 = *(const LAS bf16x8*)(kp + 64 * 72 + (ks + 1) * 16); qa2 = qsp[(ks + 1) * 64]; qb2 = qsp[(4 + ks + 1) * 64];
;                         __builtin_amdgcn_sched_group_barrier(0x100, 4, 0); }
;                     s0 = __builtin_amdgcn_mfma_f32_32x32x16_bf16(ka, qa, s0, 0, 0, 0);
;                     s1 = __builtin_amdgcn_mfma_f32_32x32x16_bf16(kb, qb, s1, 0, 0, 0);
;                     __builtin_amdgcn_sched_group_barrier(0x008, 2, 0);
;                     ka = ka2; kb = kb2; qa = qa2; qb = qb2; }
;             }
.LBB0_238:
	s_add_i32 s18, s58, 0xffffff70
	s_cmp_gt_i32 s18, s35
	s_cbranch_scc1 .LBB0_226
	ds_read_b128 v[138:141], v199 offset:4608
	ds_read_b128 v[204:207], v199 offset:13824
	ds_read_b128 v[218:221], v189
	ds_read_b128 v[222:225], v189 offset:4096
	v_xor_b32_e32 v144, 0x80000000, v190
	v_xor_b32_e32 v128, 0x80000000, v191
	v_mov_b32_e32 v145, v144
	v_mov_b64_e32 v[146:147], v[144:145]
	v_mov_b64_e32 v[148:149], v[144:145]
	v_mov_b64_e32 v[150:151], v[144:145]
	v_mov_b64_e32 v[152:153], v[144:145]
	v_mov_b64_e32 v[154:155], v[144:145]
	v_mov_b64_e32 v[156:157], v[144:145]
	v_mov_b64_e32 v[158:159], v[144:145]
	v_mov_b32_e32 v129, v128
	v_mov_b64_e32 v[130:131], v[128:129]
	v_mov_b64_e32 v[132:133], v[128:129]
	v_mov_b64_e32 v[134:135], v[128:129]
	v_mov_b64_e32 v[136:137], v[128:129]
	ds_read_b128 v[226:229], v199 offset:4640
	ds_read_b128 v[230:233], v199 offset:13856
	ds_read_b128 v[234:237], v189 offset:1024
	ds_read_b128 v[238:241], v189 offset:5120
	s_waitcnt lgkmcnt(5)
	v_mfma_f32_32x32x16_bf16 v[144:159], v[138:141], v[218:221], v[144:159]
	v_mov_b64_e32 v[142:143], v[128:129]
	v_mov_b64_e32 v[138:139], v[128:129]
	v_mov_b64_e32 v[140:141], v[128:129]
	s_cmp_le_i32 s58, s31
	s_waitcnt lgkmcnt(4)
	v_mfma_f32_32x32x16_bf16 v[128:143], v[204:207], v[222:225], v[128:143]
	ds_read_b128 v[204:207], v199 offset:4672
	ds_read_b128 v[218:221], v199 offset:13888
	ds_read_b128 v[222:225], v189 offset:2048
	ds_read_b128 v[212:215], v189 offset:6144
	s_waitcnt lgkmcnt(5)
	v_mfma_f32_32x32x16_bf16 v[144:159], v[226:229], v[234:237], v[144:159]
	s_waitcnt lgkmcnt(4)
	v_mfma_f32_32x32x16_bf16 v[128:143], v[230:233], v[238:241], v[128:143]
	ds_read_b128 v[226:229], v199 offset:4704
	ds_read_b128 v[230:233], v199 offset:13920
	ds_read_b128 v[234:237], v189 offset:3072
	ds_read_b128 v[238:241], v189 offset:7168
	s_waitcnt lgkmcnt(5)
	v_mfma_f32_32x32x16_bf16 v[144:159], v[204:207], v[222:225], v[144:159]
	s_cbranch_scc0 .Lqk_diag1
	s_waitcnt lgkmcnt(1)
	v_mfma_f32_32x32x16_bf16 v[144:159], v[226:229], v[234:237], v[144:159]
	v_add3_u32 v243, s60, v193, v192
	ds_read_b128 v[222:225], v243 offset:23104
	ds_read_b128 v[226:229], v243 offset:23136
	v_mfma_f32_32x32x16_bf16 v[128:143], v[218:221], v[212:215], v[128:143]
	s_waitcnt lgkmcnt(2)
	v_mfma_f32_32x32x16_bf16 v[128:143], v[230:233], v[238:241], v[128:143]
	ds_read_b128 v[230:233], v243 offset:27712
	ds_read_b128 v[234:237], v243 offset:27744
	ds_read_b128 v[238:241], v243 offset:32320
	ds_read_b128 v[212:215], v243 offset:18496
	ds_read_b128 v[200:203], v243 offset:18528
	s_nop 1
